# stack: hand-written W_eff prologue loop + shorter QK->rowmax chain (permlane32_swap, trimmed pads) + counted K/V prefetch waits + prio
# speedup vs baseline: 1.0097x; 1.0083x over previous
; DEVI const float* IN(int i) { return *(const float* const __attribute__((address_space(4)))*)(kargs() + 8 * i); }
; DEVI void prologue(int wv, LAS unsigned char* lds) {
;     ...
;         const float* wpool = IN(14); const float* pscale = IN(15); const float* wpo = IN(16);
;         for (size_t it = gt; it < (size_t)2 * 65536; it += NGT) {
;             const int l = (int)(it >> 16), r = (int)(it & 65535), kc = r >> 10, n = r & 1023, g = kc >> 4, c0 = (kc & 15) * 8;
;             const float* wp = wpool + (size_t)l * 4 * 128 * 128 + ((size_t)g * 128 + c0) * 128;
;             const float* ps = pscale + l * 512 + g * 128;
;             const float* wo = wpo + (size_t)l * 512 * 1024 + (size_t)g * 128 * 1024 + n;
;             float a0 = 0.f, a1 = 0.f, a2 = 0.f, a3 = 0.f, a4 = 0.f, a5 = 0.f, a6 = 0.f, a7 = 0.f;
; #pragma unroll 16
;             for (int e = 0; e < 128; ++e) { const float x = wo[(size_t)e * 1024] * ps[e];
;                 a0 += wp[e] * x; a1 += wp[128 + e] * x; a2 += wp[256 + e] * x; a3 += wp[384 + e] * x; a4 += wp[512 + e] * x; a5 += wp[640 + e] * x; a6 += wp[768 + e] * x; a7 += wp[896 + e] * x; }
.LBB0_331:
	s_or_b64 exec, exec, s[8:9]
	s_mov_b64 s[8:9], 0x20000
	s_mov_b64 s[2:3], s[0:1]
	s_mov_b64 s[24:25], s[0:1]
	s_mov_b64 s[26:27], s[0:1]
	v_cmp_gt_u64_e32 vcc, s[8:9], v[68:69]
	s_and_saveexec_b64 s[8:9], vcc
	s_cbranch_execz .LBB0_336
	s_load_dwordx2 s[28:29], s[0:1], 0x80
	s_load_dwordx2 s[10:11], s[0:1], 0x70
	s_load_dwordx2 s[12:13], s[0:1], 0x78
	v_and_b32_e32 v58, 63, v64
	v_lshrrev_b32_e32 v0, 6, v64
	v_mov_b32_e32 v1, 0
	v_readfirstlane_b32 s15, v68
	v_readfirstlane_b32 s5, v0
	v_lshlrev_b32_e32 v61, 3, v58
	s_mulk_i32 s5, 0x2100
	v_add_u32_e32 v59, s5, v61
	v_mov_b32_e32 v60, s5
	s_waitcnt lgkmcnt(0)
.Lweff_outer:
	s_bfe_u32 s2, s15, 0x3000e
	s_bfe_u32 s3, s15, 0x4000a
	s_lshl_b32 s24, s2, 16
	s_lshl_b32 s25, s3, 12
	s_add_i32 s24, s24, s25
	s_add_u32 s26, s10, s24
	s_addc_u32 s27, s11, 0
	s_lshl_b32 s24, s2, 9
	s_add_u32 s30, s12, s24
	s_addc_u32 s31, s13, 0
	global_load_dwordx2 v[40:41], v61, s[26:27]
	global_load_dwordx2 v[42:43], v61, s[26:27] offset:512
	global_load_dwordx2 v[44:45], v61, s[26:27] offset:1024
	global_load_dwordx2 v[46:47], v61, s[26:27] offset:1536
	global_load_dwordx2 v[48:49], v61, s[26:27] offset:2048
	global_load_dwordx2 v[50:51], v61, s[26:27] offset:2560
	global_load_dwordx2 v[52:53], v61, s[26:27] offset:3072
	global_load_dwordx2 v[54:55], v61, s[26:27] offset:3584
	global_load_dwordx2 v[56:57], v61, s[30:31]
	s_and_b32 s24, s15, 0x3c0
	v_add_lshl_u32 v62, v58, s24, 2
	v_lshlrev_b32_e32 v63, 8, v62
	s_lshl_b32 s24, s2, 19
	s_add_u32 s34, s28, s24
	s_addc_u32 s35, s29, 0
	v_mov_b32_e32 v2, 0
	v_mov_b32_e32 v3, 0
	v_mov_b32_e32 v4, 0
	v_mov_b32_e32 v5, 0
	v_mov_b32_e32 v6, 0
	v_mov_b32_e32 v7, 0
	v_mov_b32_e32 v8, 0
	v_mov_b32_e32 v9, 0
	global_load_dword v70, v62, s[34:35]
	s_add_u32 s34, s34, 0x1000
	s_addc_u32 s35, s35, 0
	global_load_dword v71, v62, s[34:35]
	s_add_u32 s34, s34, 0x1000
	s_addc_u32 s35, s35, 0
	global_load_dword v72, v62, s[34:35]
	s_add_u32 s34, s34, 0x1000
	s_addc_u32 s35, s35, 0
	global_load_dword v73, v62, s[34:35]
	s_add_u32 s34, s34, 0x1000
	s_addc_u32 s35, s35, 0
	global_load_dword v74, v62, s[34:35]
	s_add_u32 s34, s34, 0x1000
	s_addc_u32 s35, s35, 0
	global_load_dword v75, v62, s[34:35]
	s_add_u32 s34, s34, 0x1000
	s_addc_u32 s35, s35, 0
	global_load_dword v76, v62, s[34:35]
	s_add_u32 s34, s34, 0x1000
	s_addc_u32 s35, s35, 0
	global_load_dword v77, v62, s[34:35]
	s_add_u32 s34, s34, 0x1000
	s_addc_u32 s35, s35, 0
	global_load_dword v78, v62, s[34:35]
	s_add_u32 s34, s34, 0x1000
	s_addc_u32 s35, s35, 0
	global_load_dword v79, v62, s[34:35]
	s_add_u32 s34, s34, 0x1000
	s_addc_u32 s35, s35, 0
	global_load_dword v80, v62, s[34:35]
	s_add_u32 s34, s34, 0x1000
	s_addc_u32 s35, s35, 0
	global_load_dword v81, v62, s[34:35]
	s_add_u32 s34, s34, 0x1000
	s_addc_u32 s35, s35, 0
	global_load_dword v82, v62, s[34:35]
	s_add_u32 s34, s34, 0x1000
	s_addc_u32 s35, s35, 0
	global_load_dword v83, v62, s[34:35]
	s_add_u32 s34, s34, 0x1000
	s_addc_u32 s35, s35, 0
	global_load_dword v84, v62, s[34:35]
	s_add_u32 s34, s34, 0x1000
	s_addc_u32 s35, s35, 0
	global_load_dword v85, v62, s[34:35]
	s_add_u32 s34, s34, 0x1000
	s_addc_u32 s35, s35, 0
	s_waitcnt vmcnt(16)
	ds_write_b64 v59, v[40:41]
	ds_write_b64 v59, v[42:43] offset:512
	ds_write_b64 v59, v[44:45] offset:1024
	ds_write_b64 v59, v[46:47] offset:1536
	ds_write_b64 v59, v[48:49] offset:2048
	ds_write_b64 v59, v[50:51] offset:2560
	ds_write_b64 v59, v[52:53] offset:3072
	ds_write_b64 v59, v[54:55] offset:3584
	ds_write_b64 v59, v[56:57] offset:4096
	s_waitcnt lgkmcnt(0)
	ds_read_b128 v[134:137], v60 offset:4096
	ds_read_b128 v[138:141], v60 offset:0
	ds_read_b128 v[142:145], v60 offset:512
	ds_read_b128 v[146:149], v60 offset:1024
	ds_read_b128 v[150:153], v60 offset:1536
	ds_read_b128 v[154:157], v60 offset:2048
	ds_read_b128 v[158:161], v60 offset:2560
	ds_read_b128 v[162:165], v60 offset:3072
	ds_read_b128 v[166:169], v60 offset:3584
	s_mov_b32 s25, 0
.Lweff_inner:
	global_load_dword v86, v62, s[34:35]
	s_add_u32 s34, s34, 0x1000
	s_addc_u32 s35, s35, 0
	global_load_dword v87, v62, s[34:35]
	s_add_u32 s34, s34, 0x1000
	s_addc_u32 s35, s35, 0
	global_load_dword v88, v62, s[34:35]
	s_add_u32 s34, s34, 0x1000
	s_addc_u32 s35, s35, 0
	global_load_dword v89, v62, s[34:35]
	s_add_u32 s34, s34, 0x1000
	s_addc_u32 s35, s35, 0
	global_load_dword v90, v62, s[34:35]
	s_add_u32 s34, s34, 0x1000
	s_addc_u32 s35, s35, 0
	global_load_dword v91, v62, s[34:35]
	s_add_u32 s34, s34, 0x1000
	s_addc_u32 s35, s35, 0
	global_load_dword v92, v62, s[34:35]
	s_add_u32 s34, s34, 0x1000
	s_addc_u32 s35, s35, 0
	global_load_dword v93, v62, s[34:35]
	s_add_u32 s34, s34, 0x1000
	s_addc_u32 s35, s35, 0
	global_load_dword v94, v62, s[34:35]
	s_add_u32 s34, s34, 0x1000
	s_addc_u32 s35, s35, 0
	global_load_dword v95, v62, s[34:35]
	s_add_u32 s34, s34, 0x1000
	s_addc_u32 s35, s35, 0
	global_load_dword v96, v62, s[34:35]
	s_add_u32 s34, s34, 0x1000
	s_addc_u32 s35, s35, 0
	global_load_dword v97, v62, s[34:35]
	s_add_u32 s34, s34, 0x1000
	s_addc_u32 s35, s35, 0
	global_load_dword v98, v62, s[34:35]
	s_add_u32 s34, s34, 0x1000
	s_addc_u32 s35, s35, 0
	global_load_dword v99, v62, s[34:35]
	s_add_u32 s34, s34, 0x1000
	s_addc_u32 s35, s35, 0
	global_load_dword v100, v62, s[34:35]
	s_add_u32 s34, s34, 0x1000
	s_addc_u32 s35, s35, 0
	global_load_dword v101, v62, s[34:35]
	s_add_u32 s34, s34, 0x1000
	s_addc_u32 s35, s35, 0
	s_waitcnt vmcnt(16)
	ds_read_b128 v[10:13], v60 offset:4112
	ds_read_b128 v[14:17], v60 offset:16
	ds_read_b128 v[18:21], v60 offset:528
	ds_read_b128 v[22:25], v60 offset:1040
	ds_read_b128 v[26:29], v60 offset:1552
	ds_read_b128 v[170:173], v60 offset:2064
	ds_read_b128 v[174:177], v60 offset:2576
	ds_read_b128 v[178:181], v60 offset:3088
	ds_read_b128 v[182:185], v60 offset:3600
	s_waitcnt lgkmcnt(9)
; DEVI void prologue(int wv, LAS unsigned char* lds) {
;     ...
; #pragma unroll 16
;             for (int e = 0; e < 128; ++e) { const float x = wo[(size_t)e * 1024] * ps[e];
;                 a0 += wp[e] * x; a1 += wp[128 + e] * x; a2 += wp[256 + e] * x; a3 += wp[384 + e] * x; a4 += wp[512 + e] * x; a5 += wp[640 + e] * x; a6 += wp[768 + e] * x; a7 += wp[896 + e] * x; }
	v_mul_f32_e32 v0, v70, v134
	v_fmac_f32_e32 v2, v138, v0
	v_fmac_f32_e32 v3, v142, v0
	v_fmac_f32_e32 v4, v146, v0
	v_fmac_f32_e32 v5, v150, v0
	v_fmac_f32_e32 v6, v154, v0
	v_fmac_f32_e32 v7, v158, v0
	v_fmac_f32_e32 v8, v162, v0
	v_fmac_f32_e32 v9, v166, v0
	v_mul_f32_e32 v0, v71, v135
	v_fmac_f32_e32 v2, v139, v0
	v_fmac_f32_e32 v3, v143, v0
	v_fmac_f32_e32 v4, v147, v0
	v_fmac_f32_e32 v5, v151, v0
	v_fmac_f32_e32 v6, v155, v0
	v_fmac_f32_e32 v7, v159, v0
	v_fmac_f32_e32 v8, v163, v0
	v_fmac_f32_e32 v9, v167, v0
	v_mul_f32_e32 v0, v72, v136
	v_fmac_f32_e32 v2, v140, v0
	v_fmac_f32_e32 v3, v144, v0
	v_fmac_f32_e32 v4, v148, v0
	v_fmac_f32_e32 v5, v152, v0
	v_fmac_f32_e32 v6, v156, v0
	v_fmac_f32_e32 v7, v160, v0
	v_fmac_f32_e32 v8, v164, v0
	v_fmac_f32_e32 v9, v168, v0
	v_mul_f32_e32 v0, v73, v137
	v_fmac_f32_e32 v2, v141, v0
	v_fmac_f32_e32 v3, v145, v0
	v_fmac_f32_e32 v4, v149, v0
	v_fmac_f32_e32 v5, v153, v0
	v_fmac_f32_e32 v6, v157, v0
	v_fmac_f32_e32 v7, v161, v0
	v_fmac_f32_e32 v8, v165, v0
	v_fmac_f32_e32 v9, v169, v0
	ds_read_b128 v[134:137], v60 offset:4128
	ds_read_b128 v[138:141], v60 offset:32
	ds_read_b128 v[142:145], v60 offset:544
	ds_read_b128 v[146:149], v60 offset:1056
	ds_read_b128 v[150:153], v60 offset:1568
	ds_read_b128 v[154:157], v60 offset:2080
	ds_read_b128 v[158:161], v60 offset:2592
	ds_read_b128 v[162:165], v60 offset:3104
	ds_read_b128 v[166:169], v60 offset:3616
	s_waitcnt lgkmcnt(9)
	v_mul_f32_e32 v0, v74, v10
	v_fmac_f32_e32 v2, v14, v0
	v_fmac_f32_e32 v3, v18, v0
	v_fmac_f32_e32 v4, v22, v0
	v_fmac_f32_e32 v5, v26, v0
	v_fmac_f32_e32 v6, v170, v0
	v_fmac_f32_e32 v7, v174, v0
	v_fmac_f32_e32 v8, v178, v0
	v_fmac_f32_e32 v9, v182, v0
	v_mul_f32_e32 v0, v75, v11
	v_fmac_f32_e32 v2, v15, v0
	v_fmac_f32_e32 v3, v19, v0
	v_fmac_f32_e32 v4, v23, v0
	v_fmac_f32_e32 v5, v27, v0
	v_fmac_f32_e32 v6, v171, v0
	v_fmac_f32_e32 v7, v175, v0
	v_fmac_f32_e32 v8, v179, v0
	v_fmac_f32_e32 v9, v183, v0
	v_mul_f32_e32 v0, v76, v12
	v_fmac_f32_e32 v2, v16, v0
	v_fmac_f32_e32 v3, v20, v0
	v_fmac_f32_e32 v4, v24, v0
	v_fmac_f32_e32 v5, v28, v0
	v_fmac_f32_e32 v6, v172, v0
	v_fmac_f32_e32 v7, v176, v0
	v_fmac_f32_e32 v8, v180, v0
	v_fmac_f32_e32 v9, v184, v0
	v_mul_f32_e32 v0, v77, v13
	v_fmac_f32_e32 v2, v17, v0
	v_fmac_f32_e32 v3, v21, v0
	v_fmac_f32_e32 v4, v25, v0
	v_fmac_f32_e32 v5, v29, v0
	v_fmac_f32_e32 v6, v173, v0
	v_fmac_f32_e32 v7, v177, v0
	v_fmac_f32_e32 v8, v181, v0
	v_fmac_f32_e32 v9, v185, v0
	ds_read_b128 v[10:13], v60 offset:4144
	ds_read_b128 v[14:17], v60 offset:48
	ds_read_b128 v[18:21], v60 offset:560
	ds_read_b128 v[22:25], v60 offset:1072
	ds_read_b128 v[26:29], v60 offset:1584
	ds_read_b128 v[170:173], v60 offset:2096
	ds_read_b128 v[174:177], v60 offset:2608
	ds_read_b128 v[178:181], v60 offset:3120
	ds_read_b128 v[182:185], v60 offset:3632
	s_waitcnt lgkmcnt(9)
	v_mul_f32_e32 v0, v78, v134
	v_fmac_f32_e32 v2, v138, v0
	v_fmac_f32_e32 v3, v142, v0
	v_fmac_f32_e32 v4, v146, v0
	v_fmac_f32_e32 v5, v150, v0
	v_fmac_f32_e32 v6, v154, v0
	v_fmac_f32_e32 v7, v158, v0
	v_fmac_f32_e32 v8, v162, v0
	v_fmac_f32_e32 v9, v166, v0
	v_mul_f32_e32 v0, v79, v135
	v_fmac_f32_e32 v2, v139, v0
	v_fmac_f32_e32 v3, v143, v0
	v_fmac_f32_e32 v4, v147, v0
	v_fmac_f32_e32 v5, v151, v0
	v_fmac_f32_e32 v6, v155, v0
	v_fmac_f32_e32 v7, v159, v0
	v_fmac_f32_e32 v8, v163, v0
	v_fmac_f32_e32 v9, v167, v0
	v_mul_f32_e32 v0, v80, v136
	v_fmac_f32_e32 v2, v140, v0
	v_fmac_f32_e32 v3, v144, v0
	v_fmac_f32_e32 v4, v148, v0
	v_fmac_f32_e32 v5, v152, v0
	v_fmac_f32_e32 v6, v156, v0
	v_fmac_f32_e32 v7, v160, v0
	v_fmac_f32_e32 v8, v164, v0
	v_fmac_f32_e32 v9, v168, v0
	v_mul_f32_e32 v0, v81, v137
	v_fmac_f32_e32 v2, v141, v0
	v_fmac_f32_e32 v3, v145, v0
	v_fmac_f32_e32 v4, v149, v0
	v_fmac_f32_e32 v5, v153, v0
	v_fmac_f32_e32 v6, v157, v0
	v_fmac_f32_e32 v7, v161, v0
	v_fmac_f32_e32 v8, v165, v0
	v_fmac_f32_e32 v9, v169, v0
	ds_read_b128 v[134:137], v60 offset:4160
	ds_read_b128 v[138:141], v60 offset:64
	ds_read_b128 v[142:145], v60 offset:576
	ds_read_b128 v[146:149], v60 offset:1088
	ds_read_b128 v[150:153], v60 offset:1600
	ds_read_b128 v[154:157], v60 offset:2112
	ds_read_b128 v[158:161], v60 offset:2624
	ds_read_b128 v[162:165], v60 offset:3136
	ds_read_b128 v[166:169], v60 offset:3648
	s_waitcnt lgkmcnt(9)
	v_mul_f32_e32 v0, v82, v10
	v_fmac_f32_e32 v2, v14, v0
	v_fmac_f32_e32 v3, v18, v0
	v_fmac_f32_e32 v4, v22, v0
	v_fmac_f32_e32 v5, v26, v0
	v_fmac_f32_e32 v6, v170, v0
	v_fmac_f32_e32 v7, v174, v0
	v_fmac_f32_e32 v8, v178, v0
	v_fmac_f32_e32 v9, v182, v0
	v_mul_f32_e32 v0, v83, v11
	v_fmac_f32_e32 v2, v15, v0
	v_fmac_f32_e32 v3, v19, v0
	v_fmac_f32_e32 v4, v23, v0
	v_fmac_f32_e32 v5, v27, v0
	v_fmac_f32_e32 v6, v171, v0
	v_fmac_f32_e32 v7, v175, v0
	v_fmac_f32_e32 v8, v179, v0
	v_fmac_f32_e32 v9, v183, v0
	v_mul_f32_e32 v0, v84, v12
	v_fmac_f32_e32 v2, v16, v0
	v_fmac_f32_e32 v3, v20, v0
	v_fmac_f32_e32 v4, v24, v0
	v_fmac_f32_e32 v5, v28, v0
	v_fmac_f32_e32 v6, v172, v0
	v_fmac_f32_e32 v7, v176, v0
	v_fmac_f32_e32 v8, v180, v0
	v_fmac_f32_e32 v9, v184, v0
	v_mul_f32_e32 v0, v85, v13
	v_fmac_f32_e32 v2, v17, v0
	v_fmac_f32_e32 v3, v21, v0
	v_fmac_f32_e32 v4, v25, v0
	v_fmac_f32_e32 v5, v29, v0
	v_fmac_f32_e32 v6, v173, v0
	v_fmac_f32_e32 v7, v177, v0
	v_fmac_f32_e32 v8, v181, v0
	v_fmac_f32_e32 v9, v185, v0
	s_cmp_eq_u32 s25, 3
	s_cbranch_scc1 .Lweff_last
	global_load_dword v70, v62, s[34:35]
	s_add_u32 s34, s34, 0x1000
	s_addc_u32 s35, s35, 0
	global_load_dword v71, v62, s[34:35]
	s_add_u32 s34, s34, 0x1000
	s_addc_u32 s35, s35, 0
	global_load_dword v72, v62, s[34:35]
	s_add_u32 s34, s34, 0x1000
	s_addc_u32 s35, s35, 0
	global_load_dword v73, v62, s[34:35]
	s_add_u32 s34, s34, 0x1000
	s_addc_u32 s35, s35, 0
	global_load_dword v74, v62, s[34:35]
	s_add_u32 s34, s34, 0x1000
	s_addc_u32 s35, s35, 0
	global_load_dword v75, v62, s[34:35]
	s_add_u32 s34, s34, 0x1000
	s_addc_u32 s35, s35, 0
	global_load_dword v76, v62, s[34:35]
	s_add_u32 s34, s34, 0x1000
	s_addc_u32 s35, s35, 0
	global_load_dword v77, v62, s[34:35]
	s_add_u32 s34, s34, 0x1000
	s_addc_u32 s35, s35, 0
	global_load_dword v78, v62, s[34:35]
	s_add_u32 s34, s34, 0x1000
	s_addc_u32 s35, s35, 0
	global_load_dword v79, v62, s[34:35]
	s_add_u32 s34, s34, 0x1000
	s_addc_u32 s35, s35, 0
	global_load_dword v80, v62, s[34:35]
	s_add_u32 s34, s34, 0x1000
	s_addc_u32 s35, s35, 0
	global_load_dword v81, v62, s[34:35]
	s_add_u32 s34, s34, 0x1000
	s_addc_u32 s35, s35, 0
	global_load_dword v82, v62, s[34:35]
	s_add_u32 s34, s34, 0x1000
	s_addc_u32 s35, s35, 0
	global_load_dword v83, v62, s[34:35]
	s_add_u32 s34, s34, 0x1000
	s_addc_u32 s35, s35, 0
	global_load_dword v84, v62, s[34:35]
	s_add_u32 s34, s34, 0x1000
	s_addc_u32 s35, s35, 0
	global_load_dword v85, v62, s[34:35]
	s_add_u32 s34, s34, 0x1000
	s_addc_u32 s35, s35, 0
	s_waitcnt vmcnt(16)
	s_branch .Lweff_b

; DEVI unsigned cvtpk(float lo, float hi) { f32x2_t v = {lo, hi}; bf16x2_t b = __builtin_convertvector(v, bf16x2_t); return __builtin_bit_cast(unsigned, b); }
; DEVI void prologue(int wv, LAS unsigned char* lds) {
;     ...
; #pragma unroll 16
;             for (int e = 0; e < 128; ++e) { const float x = wo[(size_t)e * 1024] * ps[e];
;                 a0 += wp[e] * x; a1 += wp[128 + e] * x; a2 += wp[256 + e] * x; a3 += wp[384 + e] * x; a4 += wp[512 + e] * x; a5 += wp[640 + e] * x; a6 += wp[768 + e] * x; a7 += wp[896 + e] * x; }
;             u32x4 o; o.x = cvtpk(a0, a1); o.y = cvtpk(a2, a3); o.z = cvtpk(a4, a5); o.w = cvtpk(a6, a7);
;             *(u32x4*)((bf16_t*)(ws + O_W + (size_t)l * W_LAYER + W_EFF) + (size_t)n * 512 + g * 128 + c0) = o;
;         }
.Lweff_b:
	ds_read_b128 v[10:13], v60 offset:4176
	ds_read_b128 v[14:17], v60 offset:80
	ds_read_b128 v[18:21], v60 offset:592
	ds_read_b128 v[22:25], v60 offset:1104
	ds_read_b128 v[26:29], v60 offset:1616
	ds_read_b128 v[170:173], v60 offset:2128
	ds_read_b128 v[174:177], v60 offset:2640
	ds_read_b128 v[178:181], v60 offset:3152
	ds_read_b128 v[182:185], v60 offset:3664
	s_waitcnt lgkmcnt(9)
	v_mul_f32_e32 v0, v86, v134
	v_fmac_f32_e32 v2, v138, v0
	v_fmac_f32_e32 v3, v142, v0
	v_fmac_f32_e32 v4, v146, v0
	v_fmac_f32_e32 v5, v150, v0
	v_fmac_f32_e32 v6, v154, v0
	v_fmac_f32_e32 v7, v158, v0
	v_fmac_f32_e32 v8, v162, v0
	v_fmac_f32_e32 v9, v166, v0
	v_mul_f32_e32 v0, v87, v135
	v_fmac_f32_e32 v2, v139, v0
	v_fmac_f32_e32 v3, v143, v0
	v_fmac_f32_e32 v4, v147, v0
	v_fmac_f32_e32 v5, v151, v0
	v_fmac_f32_e32 v6, v155, v0
	v_fmac_f32_e32 v7, v159, v0
	v_fmac_f32_e32 v8, v163, v0
	v_fmac_f32_e32 v9, v167, v0
	v_mul_f32_e32 v0, v88, v136
	v_fmac_f32_e32 v2, v140, v0
	v_fmac_f32_e32 v3, v144, v0
	v_fmac_f32_e32 v4, v148, v0
	v_fmac_f32_e32 v5, v152, v0
	v_fmac_f32_e32 v6, v156, v0
	v_fmac_f32_e32 v7, v160, v0
	v_fmac_f32_e32 v8, v164, v0
	v_fmac_f32_e32 v9, v168, v0
	v_mul_f32_e32 v0, v89, v137
	v_fmac_f32_e32 v2, v141, v0
	v_fmac_f32_e32 v3, v145, v0
	v_fmac_f32_e32 v4, v149, v0
	v_fmac_f32_e32 v5, v153, v0
	v_fmac_f32_e32 v6, v157, v0
	v_fmac_f32_e32 v7, v161, v0
	v_fmac_f32_e32 v8, v165, v0
	v_fmac_f32_e32 v9, v169, v0
	ds_read_b128 v[134:137], v60 offset:4192
	ds_read_b128 v[138:141], v60 offset:96
	ds_read_b128 v[142:145], v60 offset:608
	ds_read_b128 v[146:149], v60 offset:1120
	ds_read_b128 v[150:153], v60 offset:1632
	ds_read_b128 v[154:157], v60 offset:2144
	ds_read_b128 v[158:161], v60 offset:2656
	ds_read_b128 v[162:165], v60 offset:3168
	ds_read_b128 v[166:169], v60 offset:3680
	s_waitcnt lgkmcnt(9)
	v_mul_f32_e32 v0, v90, v10
	v_fmac_f32_e32 v2, v14, v0
	v_fmac_f32_e32 v3, v18, v0
	v_fmac_f32_e32 v4, v22, v0
	v_fmac_f32_e32 v5, v26, v0
	v_fmac_f32_e32 v6, v170, v0
	v_fmac_f32_e32 v7, v174, v0
	v_fmac_f32_e32 v8, v178, v0
	v_fmac_f32_e32 v9, v182, v0
	v_mul_f32_e32 v0, v91, v11
	v_fmac_f32_e32 v2, v15, v0
	v_fmac_f32_e32 v3, v19, v0
	v_fmac_f32_e32 v4, v23, v0
	v_fmac_f32_e32 v5, v27, v0
	v_fmac_f32_e32 v6, v171, v0
	v_fmac_f32_e32 v7, v175, v0
	v_fmac_f32_e32 v8, v179, v0
	v_fmac_f32_e32 v9, v183, v0
	v_mul_f32_e32 v0, v92, v12
	v_fmac_f32_e32 v2, v16, v0
	v_fmac_f32_e32 v3, v20, v0
	v_fmac_f32_e32 v4, v24, v0
	v_fmac_f32_e32 v5, v28, v0
	v_fmac_f32_e32 v6, v172, v0
	v_fmac_f32_e32 v7, v176, v0
	v_fmac_f32_e32 v8, v180, v0
	v_fmac_f32_e32 v9, v184, v0
	v_mul_f32_e32 v0, v93, v13
	v_fmac_f32_e32 v2, v17, v0
	v_fmac_f32_e32 v3, v21, v0
	v_fmac_f32_e32 v4, v25, v0
	v_fmac_f32_e32 v5, v29, v0
	v_fmac_f32_e32 v6, v173, v0
	v_fmac_f32_e32 v7, v177, v0
	v_fmac_f32_e32 v8, v181, v0
	v_fmac_f32_e32 v9, v185, v0
	ds_read_b128 v[10:13], v60 offset:4208
	ds_read_b128 v[14:17], v60 offset:112
	ds_read_b128 v[18:21], v60 offset:624
	ds_read_b128 v[22:25], v60 offset:1136
	ds_read_b128 v[26:29], v60 offset:1648
	ds_read_b128 v[170:173], v60 offset:2160
	ds_read_b128 v[174:177], v60 offset:2672
	ds_read_b128 v[178:181], v60 offset:3184
	ds_read_b128 v[182:185], v60 offset:3696
	s_waitcnt lgkmcnt(9)
	v_mul_f32_e32 v0, v94, v134
	v_fmac_f32_e32 v2, v138, v0
	v_fmac_f32_e32 v3, v142, v0
	v_fmac_f32_e32 v4, v146, v0
	v_fmac_f32_e32 v5, v150, v0
	v_fmac_f32_e32 v6, v154, v0
	v_fmac_f32_e32 v7, v158, v0
	v_fmac_f32_e32 v8, v162, v0
	v_fmac_f32_e32 v9, v166, v0
	v_mul_f32_e32 v0, v95, v135
	v_fmac_f32_e32 v2, v139, v0
	v_fmac_f32_e32 v3, v143, v0
	v_fmac_f32_e32 v4, v147, v0
	v_fmac_f32_e32 v5, v151, v0
	v_fmac_f32_e32 v6, v155, v0
	v_fmac_f32_e32 v7, v159, v0
	v_fmac_f32_e32 v8, v163, v0
	v_fmac_f32_e32 v9, v167, v0
	v_mul_f32_e32 v0, v96, v136
	v_fmac_f32_e32 v2, v140, v0
	v_fmac_f32_e32 v3, v144, v0
	v_fmac_f32_e32 v4, v148, v0
	v_fmac_f32_e32 v5, v152, v0
	v_fmac_f32_e32 v6, v156, v0
	v_fmac_f32_e32 v7, v160, v0
	v_fmac_f32_e32 v8, v164, v0
	v_fmac_f32_e32 v9, v168, v0
	v_mul_f32_e32 v0, v97, v137
	v_fmac_f32_e32 v2, v141, v0
	v_fmac_f32_e32 v3, v145, v0
	v_fmac_f32_e32 v4, v149, v0
	v_fmac_f32_e32 v5, v153, v0
	v_fmac_f32_e32 v6, v157, v0
	v_fmac_f32_e32 v7, v161, v0
	v_fmac_f32_e32 v8, v165, v0
	v_fmac_f32_e32 v9, v169, v0
	ds_read_b128 v[134:137], v60 offset:4224
	ds_read_b128 v[138:141], v60 offset:128
	ds_read_b128 v[142:145], v60 offset:640
	ds_read_b128 v[146:149], v60 offset:1152
	ds_read_b128 v[150:153], v60 offset:1664
	ds_read_b128 v[154:157], v60 offset:2176
	ds_read_b128 v[158:161], v60 offset:2688
	ds_read_b128 v[162:165], v60 offset:3200
	ds_read_b128 v[166:169], v60 offset:3712
	s_waitcnt lgkmcnt(9)
	v_mul_f32_e32 v0, v98, v10
	v_fmac_f32_e32 v2, v14, v0
	v_fmac_f32_e32 v3, v18, v0
	v_fmac_f32_e32 v4, v22, v0
	v_fmac_f32_e32 v5, v26, v0
	v_fmac_f32_e32 v6, v170, v0
	v_fmac_f32_e32 v7, v174, v0
	v_fmac_f32_e32 v8, v178, v0
	v_fmac_f32_e32 v9, v182, v0
	v_mul_f32_e32 v0, v99, v11
	v_fmac_f32_e32 v2, v15, v0
	v_fmac_f32_e32 v3, v19, v0
	v_fmac_f32_e32 v4, v23, v0
	v_fmac_f32_e32 v5, v27, v0
	v_fmac_f32_e32 v6, v171, v0
	v_fmac_f32_e32 v7, v175, v0
	v_fmac_f32_e32 v8, v179, v0
	v_fmac_f32_e32 v9, v183, v0
	v_mul_f32_e32 v0, v100, v12
	v_fmac_f32_e32 v2, v16, v0
	v_fmac_f32_e32 v3, v20, v0
	v_fmac_f32_e32 v4, v24, v0
	v_fmac_f32_e32 v5, v28, v0
	v_fmac_f32_e32 v6, v172, v0
	v_fmac_f32_e32 v7, v176, v0
	v_fmac_f32_e32 v8, v180, v0
	v_fmac_f32_e32 v9, v184, v0
	v_mul_f32_e32 v0, v101, v13
	v_fmac_f32_e32 v2, v17, v0
	v_fmac_f32_e32 v3, v21, v0
	v_fmac_f32_e32 v4, v25, v0
	v_fmac_f32_e32 v5, v29, v0
	v_fmac_f32_e32 v6, v173, v0
	v_fmac_f32_e32 v7, v177, v0
	v_fmac_f32_e32 v8, v181, v0
	v_fmac_f32_e32 v9, v185, v0
	v_add_u32_e32 v60, 0x80, v60
	s_add_i32 s25, s25, 1
	s_cmp_lt_u32 s25, 4
	s_cbranch_scc1 .Lweff_inner
	s_waitcnt lgkmcnt(0)
	v_subrev_u32_e32 v60, 0x200, v60
	v_cvt_pk_bf16_f32 v10, v2, v3
	v_cvt_pk_bf16_f32 v11, v4, v5
	v_cvt_pk_bf16_f32 v12, v6, v7
	v_cvt_pk_bf16_f32 v13, v8, v9
	s_lshr_b32 s24, s2, 2
	s_mul_i32 s24, s24, 0x1c10000
	s_and_b32 s25, s2, 3
	s_lshl_b32 s25, s25, 8
	s_add_i32 s24, s24, s25
	s_lshl_b32 s25, s3, 4
	s_add_i32 s24, s24, s25
	s_add_i32 s24, s24, 0xca0800
	s_add_u32 s36, s20, s24
	s_addc_u32 s37, s21, 0
	global_store_dwordx4 v63, v[10:13], s[36:37]
	s_add_u32 s15, s15, s22
	s_cmp_lt_u32 s15, 0x20000
	s_cbranch_scc1 .Lweff_outer

; #define LAS __attribute__((address_space(3)))
; DEVI float max3a(float a, float b, float c) { float r; asm("v_max3_f32 %0, %1, %2, %3" : "=v"(r) : "v"(a), "v"(b), "v"(c)); return r; }
; DEVI float max2a(float a, float b) { float r; asm("v_max_f32_e32 %0, %1, %2" : "=v"(r) : "v"(a), "v"(b)); return r; }
; #define MFMA32(a, b, c) __builtin_amdgcn_mfma_f32_32x32x16_bf16((a), (b), (c), 0, 0, 0)
; DEVI void at_compute(const LAS unsigned char* tb, int r32, int hi, const bf16x8 (&qr)[6], bool first, f32x16& negm, float& m_ref, float& l_run, f32x16& o0, f32x16& o1) {
;     const LAS unsigned char* kb = tb + r32 * 208 + hi * 16;
;     const LAS unsigned char* vb = tb + AT_KB + r32 * 144 + hi * 16;
;     f32x16 p0 = negm, p1 = negm;
;     bf16x8 kf[12];
; #pragma unroll
;     for (int d0 = 0; d0 < 6; ++d0) { kf[2 * d0] = *(const LAS bf16x8*)(kb + d0 * 32); kf[2 * d0 + 1] = *(const LAS bf16x8*)(kb + 32 * 208 + d0 * 32); }
;     __builtin_amdgcn_sched_barrier(0);
; #pragma unroll
;     for (int d0 = 0; d0 < 6; ++d0) { p0 = MFMA32(kf[2 * d0], qr[d0], p0); p1 = MFMA32(kf[2 * d0 + 1], qr[d0], p1); }
;     bf16x8 vf[8];
; #pragma unroll
;     for (int ks = 0; ks < 4; ++ks) { vf[2 * ks] = *(const LAS bf16x8*)(vb + ks * 32); vf[2 * ks + 1] = *(const LAS bf16x8*)(vb + 32 * 144 + ks * 32); }
;     __builtin_amdgcn_sched_barrier(0);
;     asm volatile("s_nop 15\n\ts_nop 7" : "+v"(p0), "+v"(p1));
;     float mxa = max3a(p0[0], p0[1], p1[0]), mxb = max3a(p0[2], p0[3], p1[1]);
;     mxa = max3a(mxa, p1[2], p1[3]);
; #pragma unroll
;     for (int r = 4; r < 16; r += 4) { mxa = max3a(mxa, p0[r], p0[r + 1]); mxb = max3a(mxb, p0[r + 2], p0[r + 3]); mxa = max3a(mxa, p1[r], p1[r + 1]); mxb = max3a(mxb, p1[r + 2], p1[r + 3]); }
;     float mx = max2a(mxa, mxb);
;     mx = max2a(mx, __shfl_xor(mx, 32));
;     if (first || __any(mx > 8.f)) {
.LBB0_1308:
	ds_read_b128 v[2:5], v177
	ds_read_b128 v[6:9], v177 offset:32
	ds_read_b128 v[10:13], v177 offset:6656
	ds_read_b128 v[144:147], v177 offset:6688
	ds_read_b128 v[148:151], v177 offset:64
	ds_read_b128 v[152:155], v177 offset:96
	ds_read_b128 v[156:159], v177 offset:6720
	ds_read_b128 v[160:163], v177 offset:6752
	ds_read_b128 v[180:183], v177 offset:128
	ds_read_b128 v[184:187], v177 offset:160
	ds_read_b128 v[188:191], v177 offset:6784
	ds_read_b128 v[192:195], v177 offset:6816
	s_cmp_eq_u32 s49, 0
	s_cselect_b64 s[64:65], -1, 0
	s_cmp_lg_u32 s49, 0
	s_waitcnt lgkmcnt(11)
	v_mfma_f32_32x32x16_bf16 v[80:95], v[2:5], v[120:123], v[48:63]
	s_waitcnt lgkmcnt(9)
	v_mfma_f32_32x32x16_bf16 v[64:79], v[10:13], v[120:123], v[48:63]
	v_mfma_f32_32x32x16_bf16 v[80:95], v[6:9], v[124:127], v[80:95]
	s_waitcnt lgkmcnt(8)
	v_mfma_f32_32x32x16_bf16 v[64:79], v[144:147], v[124:127], v[64:79]
	s_waitcnt lgkmcnt(7)
	v_mfma_f32_32x32x16_bf16 v[80:95], v[148:151], v[128:131], v[80:95]
	s_waitcnt lgkmcnt(5)
	v_mfma_f32_32x32x16_bf16 v[64:79], v[156:159], v[128:131], v[64:79]
	v_mfma_f32_32x32x16_bf16 v[80:95], v[152:155], v[132:135], v[80:95]
	s_waitcnt lgkmcnt(4)
	v_mfma_f32_32x32x16_bf16 v[64:79], v[160:163], v[132:135], v[64:79]
	ds_read_b128 v[160:163], v178 offset:13312
	ds_read_b128 v[148:151], v178 offset:13344
	ds_read_b128 v[156:159], v178 offset:17920
	ds_read_b128 v[152:155], v178 offset:17952
	ds_read_b128 v[10:13], v178 offset:13376
	ds_read_b128 v[6:9], v178 offset:13408
	ds_read_b128 v[144:147], v178 offset:17984
	ds_read_b128 v[2:5], v178 offset:18016
	s_waitcnt lgkmcnt(11)
	v_mfma_f32_32x32x16_bf16 v[80:95], v[180:183], v[136:139], v[80:95]
	s_waitcnt lgkmcnt(9)
	v_mfma_f32_32x32x16_bf16 v[64:79], v[188:191], v[136:139], v[64:79]
	v_mfma_f32_32x32x16_bf16 v[80:95], v[184:187], v[140:143], v[80:95]
	s_waitcnt lgkmcnt(8)
	v_mfma_f32_32x32x16_bf16 v[64:79], v[192:195], v[140:143], v[64:79]
	s_nop 12
	s_nop 0
	v_max3_f32 v0, v80, v81, v64
	v_max3_f32 v179, v82, v83, v65
	v_max3_f32 v0, v0, v66, v67
	v_max3_f32 v179, v179, v86, v87
	v_max3_f32 v0, v0, v84, v85
	v_max3_f32 v179, v179, v70, v71
	v_max3_f32 v0, v0, v68, v69
	v_max3_f32 v179, v179, v90, v91
	v_max3_f32 v0, v0, v88, v89
	v_max3_f32 v179, v179, v74, v75
	v_max3_f32 v0, v0, v72, v73
	v_max3_f32 v179, v179, v94, v95
	v_max3_f32 v0, v0, v92, v93
	v_max3_f32 v179, v179, v78, v79
	v_max3_f32 v0, v0, v76, v77
	v_max_f32_e32 v0, v0, v179
	v_mov_b32_e32 v179, v0
	s_nop 1
	v_permlane32_swap_b32_e32 v179, v0
	s_waitcnt lgkmcnt(0)
	v_max_f32_e32 v179, v0, v179
	s_cbranch_scc0 .LBB0_1325
	v_cmp_lt_f32_e32 vcc, s14, v179
	s_mov_b64 s[68:69], 0
	s_mov_b64 s[66:67], 0
	s_cbranch_vccz .LBB0_1311
	v_max_f32_e32 v0, v179, v1
	s_mov_b64 s[66:67], -1

; #define LAS __attribute__((address_space(3)))
; DEVI float max3a(float a, float b, float c) { float r; asm("v_max3_f32 %0, %1, %2, %3" : "=v"(r) : "v"(a), "v"(b), "v"(c)); return r; }
; DEVI float max2a(float a, float b) { float r; asm("v_max_f32_e32 %0, %1, %2" : "=v"(r) : "v"(a), "v"(b)); return r; }
; #define MFMA32(a, b, c) __builtin_amdgcn_mfma_f32_32x32x16_bf16((a), (b), (c), 0, 0, 0)
; DEVI void at_compute(const LAS unsigned char* tb, int r32, int hi, const bf16x8 (&qr)[6], bool first, f32x16& negm, float& m_ref, float& l_run, f32x16& o0, f32x16& o1) {
;     ...
; #pragma unroll
;     for (int d0 = 0; d0 < 6; ++d0) { kf[2 * d0] = *(const LAS bf16x8*)(kb + d0 * 32); kf[2 * d0 + 1] = *(const LAS bf16x8*)(kb + 32 * 208 + d0 * 32); }
;     __builtin_amdgcn_sched_barrier(0);
; #pragma unroll
;     for (int d0 = 0; d0 < 6; ++d0) { p0 = MFMA32(kf[2 * d0], qr[d0], p0); p1 = MFMA32(kf[2 * d0 + 1], qr[d0], p1); }
;     bf16x8 vf[8];
; #pragma unroll
;     for (int ks = 0; ks < 4; ++ks) { vf[2 * ks] = *(const LAS bf16x8*)(vb + ks * 32); vf[2 * ks + 1] = *(const LAS bf16x8*)(vb + 32 * 144 + ks * 32); }
;     __builtin_amdgcn_sched_barrier(0);
;     asm volatile("s_nop 15\n\ts_nop 7" : "+v"(p0), "+v"(p1));
;     float mxa = max3a(p0[0], p0[1], p1[0]), mxb = max3a(p0[2], p0[3], p1[1]);
;     mxa = max3a(mxa, p1[2], p1[3]);
; #pragma unroll
;     for (int r = 4; r < 16; r += 4) { mxa = max3a(mxa, p0[r], p0[r + 1]); mxb = max3a(mxb, p0[r + 2], p0[r + 3]); mxa = max3a(mxa, p1[r], p1[r + 1]); mxb = max3a(mxb, p1[r + 2], p1[r + 3]); }
;     float mx = max2a(mxa, mxb);
;     mx = max2a(mx, __shfl_xor(mx, 32));
;     if (first || __any(mx > 8.f)) {
;         const float d = first ? mx : max2a(mx, 0.f);
;         m_ref += d;
;         const float alpha = first ? 1.f : __builtin_amdgcn_exp2f(-d);
;         l_run *= alpha;
; #pragma unroll
;         for (int r = 0; r < 16; ++r) { p0[r] -= d; p1[r] -= d; negm[r] -= d; o0[r] *= alpha; o1[r] *= alpha; }
;     }
.LBB0_1317:
	ds_read_b128 v[2:5], v177 offset:22528
	ds_read_b128 v[6:9], v177 offset:22560
	ds_read_b128 v[10:13], v177 offset:29184
	ds_read_b128 v[144:147], v177 offset:29216
	ds_read_b128 v[148:151], v177 offset:22592
	ds_read_b128 v[152:155], v177 offset:22624
	ds_read_b128 v[156:159], v177 offset:29248
	ds_read_b128 v[160:163], v177 offset:29280
	ds_read_b128 v[180:183], v177 offset:22656
	ds_read_b128 v[184:187], v177 offset:22688
	ds_read_b128 v[188:191], v177 offset:29312
	ds_read_b128 v[192:195], v177 offset:29344
	s_waitcnt lgkmcnt(11)
	v_mfma_f32_32x32x16_bf16 v[80:95], v[2:5], v[120:123], v[48:63]
	s_waitcnt lgkmcnt(9)
	v_mfma_f32_32x32x16_bf16 v[64:79], v[10:13], v[120:123], v[48:63]
	v_mfma_f32_32x32x16_bf16 v[80:95], v[6:9], v[124:127], v[80:95]
	s_waitcnt lgkmcnt(8)
	v_mfma_f32_32x32x16_bf16 v[64:79], v[144:147], v[124:127], v[64:79]
	s_waitcnt lgkmcnt(7)
	v_mfma_f32_32x32x16_bf16 v[80:95], v[148:151], v[128:131], v[80:95]
	s_waitcnt lgkmcnt(5)
	v_mfma_f32_32x32x16_bf16 v[64:79], v[156:159], v[128:131], v[64:79]
	v_mfma_f32_32x32x16_bf16 v[80:95], v[152:155], v[132:135], v[80:95]
	s_waitcnt lgkmcnt(4)
	v_mfma_f32_32x32x16_bf16 v[64:79], v[160:163], v[132:135], v[64:79]
	ds_read_b128 v[160:163], v178 offset:35840
	ds_read_b128 v[148:151], v178 offset:35872
	ds_read_b128 v[156:159], v178 offset:40448
	ds_read_b128 v[152:155], v178 offset:40480
	ds_read_b128 v[10:13], v178 offset:35904
	ds_read_b128 v[6:9], v178 offset:35936
	ds_read_b128 v[144:147], v178 offset:40512
	ds_read_b128 v[2:5], v178 offset:40544
	s_waitcnt lgkmcnt(11)
	v_mfma_f32_32x32x16_bf16 v[80:95], v[180:183], v[136:139], v[80:95]
	s_waitcnt lgkmcnt(9)
	v_mfma_f32_32x32x16_bf16 v[64:79], v[188:191], v[136:139], v[64:79]
	v_mfma_f32_32x32x16_bf16 v[80:95], v[184:187], v[140:143], v[80:95]
	s_waitcnt lgkmcnt(8)
	v_mfma_f32_32x32x16_bf16 v[64:79], v[192:195], v[140:143], v[64:79]
	s_nop 12
	s_nop 0
	v_max3_f32 v0, v80, v81, v64
	v_max3_f32 v14, v82, v83, v65
	v_max3_f32 v0, v0, v66, v67
	v_max3_f32 v14, v14, v86, v87
	v_max3_f32 v0, v0, v84, v85
	v_max3_f32 v14, v14, v70, v71
	v_max3_f32 v0, v0, v68, v69
	v_max3_f32 v14, v14, v90, v91
	v_max3_f32 v0, v0, v88, v89
	v_max3_f32 v14, v14, v74, v75
	v_max3_f32 v0, v0, v72, v73
	v_max3_f32 v14, v14, v94, v95
	v_max3_f32 v0, v0, v92, v93
	v_max3_f32 v14, v14, v78, v79
	v_max3_f32 v0, v0, v76, v77
	v_max_f32_e32 v0, v0, v14
	v_mov_b32_e32 v14, v0
	s_nop 1
	v_permlane32_swap_b32_e32 v14, v0
	s_waitcnt lgkmcnt(0)
	v_max_f32_e32 v0, v0, v14
	s_nop 0
	v_cmp_lt_f32_e32 vcc, s14, v0
	s_cbranch_vccz .LBB0_1319
	v_max_f32_e32 v0, v0, v1
	s_nop 0
	v_exp_f32_e64 v14, -v0
	v_pk_add_f32 v[80:81], v[80:81], v[0:1] op_sel_hi:[1,0] neg_lo:[0,1] neg_hi:[0,1]
	v_pk_add_f32 v[64:65], v[64:65], v[0:1] op_sel_hi:[1,0] neg_lo:[0,1] neg_hi:[0,1]
	v_pk_add_f32 v[82:83], v[82:83], v[0:1] op_sel_hi:[1,0] neg_lo:[0,1] neg_hi:[0,1]
	v_mul_f32_e32 v176, v176, v14
	v_pk_add_f32 v[66:67], v[66:67], v[0:1] op_sel_hi:[1,0] neg_lo:[0,1] neg_hi:[0,1]
	v_pk_add_f32 v[84:85], v[84:85], v[0:1] op_sel_hi:[1,0] neg_lo:[0,1] neg_hi:[0,1]
	v_pk_add_f32 v[68:69], v[68:69], v[0:1] op_sel_hi:[1,0] neg_lo:[0,1] neg_hi:[0,1]
	v_pk_add_f32 v[86:87], v[86:87], v[0:1] op_sel_hi:[1,0] neg_lo:[0,1] neg_hi:[0,1]
	v_pk_add_f32 v[70:71], v[70:71], v[0:1] op_sel_hi:[1,0] neg_lo:[0,1] neg_hi:[0,1]
	v_pk_add_f32 v[88:89], v[88:89], v[0:1] op_sel_hi:[1,0] neg_lo:[0,1] neg_hi:[0,1]
	v_pk_add_f32 v[72:73], v[72:73], v[0:1] op_sel_hi:[1,0] neg_lo:[0,1] neg_hi:[0,1]
	v_pk_add_f32 v[90:91], v[90:91], v[0:1] op_sel_hi:[1,0] neg_lo:[0,1] neg_hi:[0,1]
	v_pk_add_f32 v[74:75], v[74:75], v[0:1] op_sel_hi:[1,0] neg_lo:[0,1] neg_hi:[0,1]
	v_pk_add_f32 v[92:93], v[92:93], v[0:1] op_sel_hi:[1,0] neg_lo:[0,1] neg_hi:[0,1]
	v_pk_add_f32 v[76:77], v[76:77], v[0:1] op_sel_hi:[1,0] neg_lo:[0,1] neg_hi:[0,1]
	v_pk_add_f32 v[94:95], v[94:95], v[0:1] op_sel_hi:[1,0] neg_lo:[0,1] neg_hi:[0,1]
	v_pk_add_f32 v[78:79], v[78:79], v[0:1] op_sel_hi:[1,0] neg_lo:[0,1] neg_hi:[0,1]
	v_sub_f32_e32 v63, v63, v0
	v_sub_f32_e32 v62, v62, v0
	v_sub_f32_e32 v61, v61, v0
	v_sub_f32_e32 v60, v60, v0
	v_sub_f32_e32 v59, v59, v0
	v_sub_f32_e32 v58, v58, v0
	v_sub_f32_e32 v57, v57, v0
	v_sub_f32_e32 v56, v56, v0
	v_sub_f32_e32 v55, v55, v0
	v_sub_f32_e32 v54, v54, v0
	v_sub_f32_e32 v53, v53, v0
	v_sub_f32_e32 v52, v52, v0
	v_sub_f32_e32 v51, v51, v0
	v_sub_f32_e32 v50, v50, v0
	v_sub_f32_e32 v49, v49, v0
	v_sub_f32_e32 v48, v48, v0
	v_pk_mul_f32 v[46:47], v[46:47], v[14:15] op_sel_hi:[1,0]
	v_pk_mul_f32 v[44:45], v[44:45], v[14:15] op_sel_hi:[1,0]
	v_pk_mul_f32 v[42:43], v[42:43], v[14:15] op_sel_hi:[1,0]
	v_pk_mul_f32 v[40:41], v[40:41], v[14:15] op_sel_hi:[1,0]
	v_pk_mul_f32 v[38:39], v[38:39], v[14:15] op_sel_hi:[1,0]
	v_pk_mul_f32 v[36:37], v[36:37], v[14:15] op_sel_hi:[1,0]
	v_pk_mul_f32 v[34:35], v[34:35], v[14:15] op_sel_hi:[1,0]
	v_pk_mul_f32 v[32:33], v[32:33], v[14:15] op_sel_hi:[1,0]
	v_pk_mul_f32 v[30:31], v[30:31], v[14:15] op_sel_hi:[1,0]
	v_pk_mul_f32 v[28:29], v[28:29], v[14:15] op_sel_hi:[1,0]
	v_pk_mul_f32 v[26:27], v[26:27], v[14:15] op_sel_hi:[1,0]
	v_pk_mul_f32 v[24:25], v[24:25], v[14:15] op_sel_hi:[1,0]
	v_pk_mul_f32 v[22:23], v[22:23], v[14:15] op_sel_hi:[1,0]
	v_pk_mul_f32 v[20:21], v[20:21], v[14:15] op_sel_hi:[1,0]
	v_pk_mul_f32 v[18:19], v[18:19], v[14:15] op_sel_hi:[1,0]
	v_pk_mul_f32 v[16:17], v[16:17], v[14:15] op_sel_hi:[1,0]
